# SwiGLU epilogue store addresses: per-row-block v_or + v_mad_i64 replaced by one 64-bit add from the first block's address
# baseline (speedup 1.0000x reference)
.LBB0_216:
	ds_read2_b32 v[156:157], v152 offset1:16
	ds_read2_b32 v[148:149], v152 offset0:32 offset1:48
	ds_read2_b32 v[146:147], v152 offset0:64 offset1:80
	ds_read2_b32 v[140:141], v152 offset0:96 offset1:112
	v_lshl_or_b32 v144, s27, 7, v153
	s_waitcnt lgkmcnt(0)
	v_mul_f32_e32 v160, 0xbfb8aa3b, v156
	v_mul_f32_e32 v156, v156, v156
	v_pk_mul_f32 v[162:163], v[130:131], v[160:161] op_sel_hi:[1,0]
	v_pk_mul_f32 v[164:165], v[128:129], v[160:161] op_sel_hi:[1,0]
	v_pk_mul_f32 v[166:167], v[126:127], v[160:161] op_sel_hi:[1,0]
	v_pk_mul_f32 v[160:161], v[124:125], v[160:161] op_sel_hi:[1,0]
	v_exp_f32_e32 v164, v164
	v_exp_f32_e32 v160, v160
	v_exp_f32_e32 v165, v165
	v_exp_f32_e32 v161, v161
	v_exp_f32_e32 v162, v162
	v_exp_f32_e32 v166, v166
	v_exp_f32_e32 v163, v163
	v_exp_f32_e32 v167, v167
	v_rcp_f32_e32 v156, v156
	v_add_u32_e32 v155, s19, v150
	v_ashrrev_i32_e32 v145, 31, v144
	v_mov_b64_e32 v[142:143], s[14:15]
	v_pk_fma_f32 v[162:163], v[156:157], v[162:163], v[156:157] op_sel_hi:[0,1,0]
	v_pk_fma_f32 v[164:165], v[156:157], v[164:165], v[156:157] op_sel_hi:[0,1,0]
	v_pk_fma_f32 v[166:167], v[156:157], v[166:167], v[156:157] op_sel_hi:[0,1,0]
	v_pk_fma_f32 v[160:161], v[156:157], v[160:161], v[156:157] op_sel_hi:[0,1,0]
	v_rcp_f32_e32 v164, v164
	v_rcp_f32_e32 v160, v160
	v_rcp_f32_e32 v165, v165
	v_rcp_f32_e32 v161, v161
	v_rcp_f32_e32 v162, v162
	v_rcp_f32_e32 v166, v166
	v_rcp_f32_e32 v163, v163
	v_rcp_f32_e32 v167, v167
	v_pk_mul_f32 v[122:123], v[130:131], v[122:123]
	v_pk_mul_f32 v[120:121], v[128:129], v[120:121]
	v_pk_mul_f32 v[118:119], v[126:127], v[118:119]
	v_pk_mul_f32 v[116:117], v[124:125], v[116:117]
	v_mad_i64_i32 v[158:159], s[26:27], v155, s90, v[142:143]
	s_mov_b32 s99, 0
	v_lshlrev_b64 v[144:145], 1, v[144:145]
	v_pk_mul_f32 v[122:123], v[122:123], v[162:163]
	v_pk_mul_f32 v[120:121], v[120:121], v[164:165]
	v_pk_mul_f32 v[124:125], v[118:119], v[166:167]
	v_pk_mul_f32 v[118:119], v[116:117], v[160:161]
	v_lshl_add_u64 v[158:159], v[158:159], 0, v[144:145]
	v_cvt_pk_bf16_f32 v116, v120, v121
	v_cvt_pk_bf16_f32 v117, v122, v123
	v_cvt_pk_bf16_f32 v118, v118, v119
	v_cvt_pk_bf16_f32 v119, v124, v125
	global_store_dwordx4 v[158:159], v[116:119], off nt
	v_mul_f32_e32 v126, v157, v157
	v_rcp_f32_e32 v126, v126
	v_mul_f32_e32 v118, 0xbfb8aa3b, v157
	v_pk_mul_f32 v[120:121], v[114:115], v[118:119] op_sel_hi:[1,0]
	v_pk_mul_f32 v[122:123], v[112:113], v[118:119] op_sel_hi:[1,0]
	v_pk_mul_f32 v[124:125], v[110:111], v[118:119] op_sel_hi:[1,0]
	v_pk_mul_f32 v[118:119], v[108:109], v[118:119] op_sel_hi:[1,0]
	v_exp_f32_e32 v122, v122
	v_exp_f32_e32 v118, v118
	v_exp_f32_e32 v123, v123
	v_exp_f32_e32 v119, v119
	v_exp_f32_e32 v120, v120
	v_exp_f32_e32 v124, v124
	v_exp_f32_e32 v121, v121
	v_exp_f32_e32 v125, v125
	v_pk_fma_f32 v[122:123], v[126:127], v[122:123], v[126:127] op_sel_hi:[0,1,0]
	v_pk_fma_f32 v[118:119], v[126:127], v[118:119], v[126:127] op_sel_hi:[0,1,0]
	v_pk_fma_f32 v[120:121], v[126:127], v[120:121], v[126:127] op_sel_hi:[0,1,0]
	v_pk_fma_f32 v[124:125], v[126:127], v[124:125], v[126:127] op_sel_hi:[0,1,0]
	v_rcp_f32_e32 v122, v122
	v_rcp_f32_e32 v118, v118
	v_rcp_f32_e32 v123, v123
	v_rcp_f32_e32 v119, v119
	v_rcp_f32_e32 v120, v120
	v_rcp_f32_e32 v124, v124
	v_rcp_f32_e32 v121, v121
	v_rcp_f32_e32 v125, v125
	v_pk_mul_f32 v[106:107], v[114:115], v[106:107]
	v_pk_mul_f32 v[104:105], v[112:113], v[104:105]
	v_pk_mul_f32 v[102:103], v[110:111], v[102:103]
	v_pk_mul_f32 v[100:101], v[108:109], v[100:101]
	v_pk_mul_f32 v[106:107], v[106:107], v[120:121]
	v_pk_mul_f32 v[104:105], v[104:105], v[122:123]
	v_pk_mul_f32 v[108:109], v[102:103], v[124:125]
	v_pk_mul_f32 v[102:103], v[100:101], v[118:119]
	s_mov_b32 s98, 0x2c000
	v_lshl_add_u64 v[116:117], v[158:159], 0, s[98:99]
	v_cvt_pk_bf16_f32 v100, v104, v105
	v_cvt_pk_bf16_f32 v101, v106, v107
	v_cvt_pk_bf16_f32 v102, v102, v103
	v_cvt_pk_bf16_f32 v103, v108, v109
	global_store_dwordx4 v[116:117], v[100:103], off nt
	v_mul_f32_e32 v110, v148, v148
	v_rcp_f32_e32 v110, v110
	v_mul_f32_e32 v102, 0xbfb8aa3b, v148
	v_pk_mul_f32 v[104:105], v[98:99], v[102:103] op_sel_hi:[1,0]
	v_pk_mul_f32 v[106:107], v[96:97], v[102:103] op_sel_hi:[1,0]
	v_pk_mul_f32 v[108:109], v[94:95], v[102:103] op_sel_hi:[1,0]
	v_pk_mul_f32 v[102:103], v[92:93], v[102:103] op_sel_hi:[1,0]
	v_exp_f32_e32 v106, v106
	v_exp_f32_e32 v102, v102
	v_exp_f32_e32 v107, v107
	v_exp_f32_e32 v103, v103
	v_exp_f32_e32 v104, v104
	v_exp_f32_e32 v108, v108
	v_exp_f32_e32 v105, v105
	v_exp_f32_e32 v109, v109
	v_pk_fma_f32 v[106:107], v[110:111], v[106:107], v[110:111] op_sel_hi:[0,1,0]
	v_pk_fma_f32 v[102:103], v[110:111], v[102:103], v[110:111] op_sel_hi:[0,1,0]
	v_pk_fma_f32 v[104:105], v[110:111], v[104:105], v[110:111] op_sel_hi:[0,1,0]
	v_pk_fma_f32 v[108:109], v[110:111], v[108:109], v[110:111] op_sel_hi:[0,1,0]
	v_rcp_f32_e32 v106, v106
	v_rcp_f32_e32 v102, v102
	v_rcp_f32_e32 v107, v107
	v_rcp_f32_e32 v103, v103
	v_rcp_f32_e32 v104, v104
	v_rcp_f32_e32 v108, v108
	v_rcp_f32_e32 v105, v105
	v_rcp_f32_e32 v109, v109
	v_pk_mul_f32 v[90:91], v[98:99], v[90:91]
	v_pk_mul_f32 v[88:89], v[96:97], v[88:89]
	v_pk_mul_f32 v[86:87], v[94:95], v[86:87]
	v_pk_mul_f32 v[84:85], v[92:93], v[84:85]
	v_pk_mul_f32 v[90:91], v[90:91], v[104:105]
	v_pk_mul_f32 v[88:89], v[88:89], v[106:107]
	v_pk_mul_f32 v[92:93], v[86:87], v[108:109]
	v_pk_mul_f32 v[86:87], v[84:85], v[102:103]
	s_mov_b32 s98, 0x58000
	v_lshl_add_u64 v[100:101], v[158:159], 0, s[98:99]
	v_cvt_pk_bf16_f32 v84, v88, v89
	v_cvt_pk_bf16_f32 v85, v90, v91
	v_cvt_pk_bf16_f32 v86, v86, v87
	v_cvt_pk_bf16_f32 v87, v92, v93
	global_store_dwordx4 v[100:101], v[84:87], off nt
	v_mul_f32_e32 v94, v149, v149
	v_rcp_f32_e32 v94, v94
	v_mul_f32_e32 v86, 0xbfb8aa3b, v149
	v_pk_mul_f32 v[88:89], v[82:83], v[86:87] op_sel_hi:[1,0]
	v_pk_mul_f32 v[90:91], v[80:81], v[86:87] op_sel_hi:[1,0]
	v_pk_mul_f32 v[92:93], v[78:79], v[86:87] op_sel_hi:[1,0]
	v_pk_mul_f32 v[86:87], v[76:77], v[86:87] op_sel_hi:[1,0]
	v_exp_f32_e32 v90, v90
	v_exp_f32_e32 v86, v86
	v_exp_f32_e32 v91, v91
	v_exp_f32_e32 v87, v87
	v_exp_f32_e32 v88, v88
	v_exp_f32_e32 v92, v92
	v_exp_f32_e32 v89, v89
	v_exp_f32_e32 v93, v93
	v_pk_fma_f32 v[90:91], v[94:95], v[90:91], v[94:95] op_sel_hi:[0,1,0]
	v_pk_fma_f32 v[86:87], v[94:95], v[86:87], v[94:95] op_sel_hi:[0,1,0]
	v_pk_fma_f32 v[88:89], v[94:95], v[88:89], v[94:95] op_sel_hi:[0,1,0]
	v_pk_fma_f32 v[92:93], v[94:95], v[92:93], v[94:95] op_sel_hi:[0,1,0]
	v_rcp_f32_e32 v90, v90
	v_rcp_f32_e32 v86, v86
	v_rcp_f32_e32 v91, v91
	v_rcp_f32_e32 v87, v87
	v_rcp_f32_e32 v88, v88
	v_rcp_f32_e32 v92, v92
	v_rcp_f32_e32 v89, v89
	v_rcp_f32_e32 v93, v93
	v_pk_mul_f32 v[74:75], v[82:83], v[74:75]
	v_pk_mul_f32 v[72:73], v[80:81], v[72:73]
	v_pk_mul_f32 v[70:71], v[78:79], v[70:71]
	v_pk_mul_f32 v[68:69], v[76:77], v[68:69]
	v_pk_mul_f32 v[74:75], v[74:75], v[88:89]
	v_pk_mul_f32 v[72:73], v[72:73], v[90:91]
	v_pk_mul_f32 v[76:77], v[70:71], v[92:93]
	v_pk_mul_f32 v[70:71], v[68:69], v[86:87]
	s_mov_b32 s98, 0x84000
	v_lshl_add_u64 v[84:85], v[158:159], 0, s[98:99]
	v_cvt_pk_bf16_f32 v68, v72, v73
	v_cvt_pk_bf16_f32 v69, v74, v75
	v_cvt_pk_bf16_f32 v70, v70, v71
	v_cvt_pk_bf16_f32 v71, v76, v77
	global_store_dwordx4 v[84:85], v[68:71], off nt
	v_mul_f32_e32 v78, v146, v146
	v_rcp_f32_e32 v78, v78
	v_mul_f32_e32 v70, 0xbfb8aa3b, v146
	v_pk_mul_f32 v[72:73], v[66:67], v[70:71] op_sel_hi:[1,0]
	v_pk_mul_f32 v[74:75], v[64:65], v[70:71] op_sel_hi:[1,0]
	v_pk_mul_f32 v[76:77], v[62:63], v[70:71] op_sel_hi:[1,0]
	v_pk_mul_f32 v[70:71], v[60:61], v[70:71] op_sel_hi:[1,0]
	v_exp_f32_e32 v74, v74
	v_exp_f32_e32 v70, v70
	v_exp_f32_e32 v75, v75
	v_exp_f32_e32 v71, v71
	v_exp_f32_e32 v72, v72
	v_exp_f32_e32 v76, v76
	v_exp_f32_e32 v73, v73
	v_exp_f32_e32 v77, v77
	v_pk_fma_f32 v[74:75], v[78:79], v[74:75], v[78:79] op_sel_hi:[0,1,0]
	v_pk_fma_f32 v[70:71], v[78:79], v[70:71], v[78:79] op_sel_hi:[0,1,0]
	v_pk_fma_f32 v[72:73], v[78:79], v[72:73], v[78:79] op_sel_hi:[0,1,0]
	v_pk_fma_f32 v[76:77], v[78:79], v[76:77], v[78:79] op_sel_hi:[0,1,0]
	v_rcp_f32_e32 v74, v74
	v_rcp_f32_e32 v70, v70
	v_rcp_f32_e32 v75, v75
	v_rcp_f32_e32 v71, v71
	v_rcp_f32_e32 v72, v72
	v_rcp_f32_e32 v76, v76
	v_rcp_f32_e32 v73, v73
	v_rcp_f32_e32 v77, v77
	v_pk_mul_f32 v[58:59], v[66:67], v[58:59]
	v_pk_mul_f32 v[56:57], v[64:65], v[56:57]
	v_pk_mul_f32 v[54:55], v[62:63], v[54:55]
	v_pk_mul_f32 v[52:53], v[60:61], v[52:53]
	v_pk_mul_f32 v[58:59], v[58:59], v[72:73]
	v_pk_mul_f32 v[56:57], v[56:57], v[74:75]
	v_pk_mul_f32 v[60:61], v[54:55], v[76:77]
	v_pk_mul_f32 v[54:55], v[52:53], v[70:71]
	s_mov_b32 s98, 0x160000
	v_lshl_add_u64 v[68:69], v[158:159], 0, s[98:99]
	v_cvt_pk_bf16_f32 v52, v56, v57
	v_cvt_pk_bf16_f32 v53, v58, v59
	v_cvt_pk_bf16_f32 v54, v54, v55
	v_cvt_pk_bf16_f32 v55, v60, v61
	global_store_dwordx4 v[68:69], v[52:55], off nt
	v_mul_f32_e32 v62, v147, v147
	v_rcp_f32_e32 v62, v62
	v_mul_f32_e32 v54, 0xbfb8aa3b, v147
	v_pk_mul_f32 v[56:57], v[50:51], v[54:55] op_sel_hi:[1,0]
	v_pk_mul_f32 v[58:59], v[48:49], v[54:55] op_sel_hi:[1,0]
	v_pk_mul_f32 v[60:61], v[46:47], v[54:55] op_sel_hi:[1,0]
	v_pk_mul_f32 v[54:55], v[44:45], v[54:55] op_sel_hi:[1,0]
	v_exp_f32_e32 v58, v58
	v_exp_f32_e32 v54, v54
	v_exp_f32_e32 v59, v59
	v_exp_f32_e32 v55, v55
	v_exp_f32_e32 v56, v56
	v_exp_f32_e32 v60, v60
	v_exp_f32_e32 v57, v57
	v_exp_f32_e32 v61, v61
	v_pk_fma_f32 v[58:59], v[62:63], v[58:59], v[62:63] op_sel_hi:[0,1,0]
	v_pk_fma_f32 v[54:55], v[62:63], v[54:55], v[62:63] op_sel_hi:[0,1,0]
	v_pk_fma_f32 v[56:57], v[62:63], v[56:57], v[62:63] op_sel_hi:[0,1,0]
	v_pk_fma_f32 v[60:61], v[62:63], v[60:61], v[62:63] op_sel_hi:[0,1,0]
	v_rcp_f32_e32 v58, v58
	v_rcp_f32_e32 v54, v54
	v_rcp_f32_e32 v59, v59
	v_rcp_f32_e32 v55, v55
	v_rcp_f32_e32 v56, v56
	v_rcp_f32_e32 v60, v60
	v_rcp_f32_e32 v57, v57
	v_rcp_f32_e32 v61, v61
	v_pk_mul_f32 v[42:43], v[50:51], v[42:43]
	v_pk_mul_f32 v[40:41], v[48:49], v[40:41]
	v_pk_mul_f32 v[38:39], v[46:47], v[38:39]
	v_pk_mul_f32 v[36:37], v[44:45], v[36:37]
	v_pk_mul_f32 v[42:43], v[42:43], v[56:57]
	v_pk_mul_f32 v[40:41], v[40:41], v[58:59]
	v_pk_mul_f32 v[44:45], v[38:39], v[60:61]
	v_pk_mul_f32 v[38:39], v[36:37], v[54:55]
	s_mov_b32 s98, 0x18c000
	v_lshl_add_u64 v[52:53], v[158:159], 0, s[98:99]
	v_cvt_pk_bf16_f32 v36, v40, v41
	v_cvt_pk_bf16_f32 v37, v42, v43
	v_cvt_pk_bf16_f32 v38, v38, v39
	v_cvt_pk_bf16_f32 v39, v44, v45
	global_store_dwordx4 v[52:53], v[36:39], off nt
	v_mul_f32_e32 v46, v140, v140
	v_rcp_f32_e32 v46, v46
	v_mul_f32_e32 v38, 0xbfb8aa3b, v140
	v_pk_mul_f32 v[40:41], v[34:35], v[38:39] op_sel_hi:[1,0]
	v_pk_mul_f32 v[42:43], v[32:33], v[38:39] op_sel_hi:[1,0]
	v_pk_mul_f32 v[44:45], v[30:31], v[38:39] op_sel_hi:[1,0]
	v_pk_mul_f32 v[38:39], v[28:29], v[38:39] op_sel_hi:[1,0]
	v_exp_f32_e32 v42, v42
	v_exp_f32_e32 v38, v38
	v_exp_f32_e32 v43, v43
	v_exp_f32_e32 v39, v39
	v_exp_f32_e32 v40, v40
	v_exp_f32_e32 v44, v44
	v_exp_f32_e32 v41, v41
	v_exp_f32_e32 v45, v45
	v_pk_fma_f32 v[42:43], v[46:47], v[42:43], v[46:47] op_sel_hi:[0,1,0]
	v_pk_fma_f32 v[38:39], v[46:47], v[38:39], v[46:47] op_sel_hi:[0,1,0]
	v_pk_fma_f32 v[40:41], v[46:47], v[40:41], v[46:47] op_sel_hi:[0,1,0]
	v_pk_fma_f32 v[44:45], v[46:47], v[44:45], v[46:47] op_sel_hi:[0,1,0]
	v_rcp_f32_e32 v42, v42
	v_rcp_f32_e32 v38, v38
	v_rcp_f32_e32 v43, v43
	v_rcp_f32_e32 v39, v39
	v_rcp_f32_e32 v40, v40
	v_rcp_f32_e32 v44, v44
	v_rcp_f32_e32 v41, v41
	v_rcp_f32_e32 v45, v45
	v_pk_mul_f32 v[26:27], v[34:35], v[26:27]
	v_pk_mul_f32 v[24:25], v[32:33], v[24:25]
	v_pk_mul_f32 v[22:23], v[30:31], v[22:23]
	v_pk_mul_f32 v[20:21], v[28:29], v[20:21]
	v_pk_mul_f32 v[26:27], v[26:27], v[40:41]
	v_pk_mul_f32 v[24:25], v[24:25], v[42:43]
	v_pk_mul_f32 v[28:29], v[22:23], v[44:45]
	v_pk_mul_f32 v[22:23], v[20:21], v[38:39]
	s_mov_b32 s98, 0x1b8000
	v_lshl_add_u64 v[36:37], v[158:159], 0, s[98:99]
	v_cvt_pk_bf16_f32 v20, v24, v25
	v_cvt_pk_bf16_f32 v21, v26, v27
	v_cvt_pk_bf16_f32 v22, v22, v23
	v_cvt_pk_bf16_f32 v23, v28, v29
	global_store_dwordx4 v[36:37], v[20:23], off nt
	v_mul_f32_e32 v30, v141, v141
	v_rcp_f32_e32 v30, v30
	v_mul_f32_e32 v22, 0xbfb8aa3b, v141
	v_pk_mul_f32 v[24:25], v[18:19], v[22:23] op_sel_hi:[1,0]
	v_pk_mul_f32 v[26:27], v[16:17], v[22:23] op_sel_hi:[1,0]
	v_pk_mul_f32 v[28:29], v[14:15], v[22:23] op_sel_hi:[1,0]
	v_pk_mul_f32 v[22:23], v[12:13], v[22:23] op_sel_hi:[1,0]
	v_exp_f32_e32 v26, v26
	v_exp_f32_e32 v22, v22
	v_exp_f32_e32 v27, v27
	v_exp_f32_e32 v23, v23
	v_exp_f32_e32 v24, v24
	v_exp_f32_e32 v28, v28
	v_exp_f32_e32 v25, v25
	v_exp_f32_e32 v29, v29
	v_pk_fma_f32 v[26:27], v[30:31], v[26:27], v[30:31] op_sel_hi:[0,1,0]
	v_pk_fma_f32 v[22:23], v[30:31], v[22:23], v[30:31] op_sel_hi:[0,1,0]
	v_pk_fma_f32 v[24:25], v[30:31], v[24:25], v[30:31] op_sel_hi:[0,1,0]
	v_pk_fma_f32 v[28:29], v[30:31], v[28:29], v[30:31] op_sel_hi:[0,1,0]
	v_rcp_f32_e32 v26, v26
	v_rcp_f32_e32 v22, v22
	v_rcp_f32_e32 v27, v27
	v_rcp_f32_e32 v23, v23
	v_rcp_f32_e32 v24, v24
	v_rcp_f32_e32 v28, v28
	v_rcp_f32_e32 v25, v25
	v_rcp_f32_e32 v29, v29
	v_pk_mul_f32 v[10:11], v[18:19], v[10:11]
	v_pk_mul_f32 v[8:9], v[16:17], v[8:9]
	v_pk_mul_f32 v[6:7], v[14:15], v[6:7]
	v_pk_mul_f32 v[4:5], v[12:13], v[4:5]
	v_pk_mul_f32 v[10:11], v[10:11], v[24:25]
	v_pk_mul_f32 v[8:9], v[8:9], v[26:27]
	v_pk_mul_f32 v[12:13], v[6:7], v[28:29]
	v_pk_mul_f32 v[6:7], v[4:5], v[22:23]
	s_mov_b32 s98, 0x1e4000
	v_lshl_add_u64 v[20:21], v[158:159], 0, s[98:99]
	v_cvt_pk_bf16_f32 v4, v8, v9
	v_cvt_pk_bf16_f32 v5, v10, v11
	v_cvt_pk_bf16_f32 v6, v6, v7
	v_cvt_pk_bf16_f32 v7, v12, v13
	s_mov_b64 s[26:27], -1
	s_andn2_b64 vcc, exec, s[34:35]
	global_store_dwordx4 v[20:21], v[4:7], off nt
	s_cbranch_vccnz .LBB0_207
	s_andn2_b64 vcc, exec, s[12:13]
	s_cbranch_vccnz .LBB0_206
	s_barrier
	s_branch .LBB0_206
